# phase prologues: one lgkmcnt wait per group of consecutive kernel-argument scalar loads instead of one per load (prologue de-serialisation)
# speedup vs baseline: 1.0086x; 1.0086x over previous
; #define LAS __attribute__((address_space(3)))
; __device__ __forceinline__ float silu_f(float x) { return x / (1.0f + __expf(-x)); }
; #define ARG_IN(i) argp(i)
; __device__ __forceinline__ void mod_phase(int j0, int j1, LAS unsigned char* lds, int vcu, int G, int tid, int wave, int lane) {
;     unsigned char* ws_ = ARG_WS; float* MOD = (float*)(ws_ + WS_MOD); const float* c = ARG_IN(1); const float* w_ada = ARG_IN(2); const float* b_ada = ARG_IN(3);
;     LAS float* part = (LAS float*)lds;
;     for (int job = j0 + vcu; job < j1; job += G) {
;         const int lm = job / 144, colbase = (job % 144) * 64, kk = lane >> 4, c4 = lane & 15;
;         f32x4 acc0 = {0.f, 0.f, 0.f, 0.f}, acc1 = {0.f, 0.f, 0.f, 0.f};
;         const float* wp = w_ada + ((size_t)lm * 1024 + wave * 128 + kk) * 9216 + colbase + 4 * c4;
; #pragma unroll 8
;         for (int i = 0; i < 32; ++i) { const int k = wave * 128 + 4 * i + kk; const f32x4 wv = *(const f32x4*)(wp + (size_t)i * 4 * 9216); const float a0 = silu_f(c[k]), a1 = silu_f(c[1024 + k]); acc0 += a0 * wv; acc1 += a1 * wv; }
.LBB0_18:
	s_lshr_b32 s0, s0, 6
	v_writelane_b32 v255, s0, 4
	s_load_dwordx2 s[0:1], s[96:97], 0x98
	s_mov_b32 s3, s2
	v_mov_b32_e32 v0, v219
	s_waitcnt lgkmcnt(0)
	s_mov_b32 s1, s71
	s_load_dwordx2 s[42:43], s[96:97], 0x88
	s_load_dwordx2 s[44:45], s[96:97], 8
	s_load_dwordx2 s[8:9], s[96:97], 16
	s_load_dwordx2 s[46:47], s[96:97], 24
	s_waitcnt lgkmcnt(0)
	s_cmp_gt_i32 s1, 31
	v_mbcnt_lo_u32_b32 v76, -1, 0
	s_cbranch_scc1 .LBB0_27
	v_mbcnt_hi_u32_b32 v3, -1, v76
	v_and_b32_e32 v5, 64, v3
	v_xor_b32_e32 v4, 16, v3
	v_add_u32_e32 v5, 64, v5
	v_cmp_lt_i32_e32 vcc, v4, v5
	v_readlane_b32 s10, v255, 4
	s_lshl_b32 s3, s10, 9
	v_cndmask_b32_e32 v4, v3, v4, vcc
	v_lshlrev_b32_e32 v33, 2, v4
	v_xor_b32_e32 v4, 32, v3
	v_cmp_lt_i32_e32 vcc, v4, v5
	s_add_i32 s3, s3, 0
	v_and_b32_e32 v32, 63, v0
	v_cndmask_b32_e32 v3, v3, v4, vcc
	v_lshlrev_b32_e32 v62, 2, v3
	v_lshlrev_b32_e32 v3, 4, v0
	v_and_b32_e32 v3, 0xf0, v3
	v_bfe_u32 v1, v0, 4, 2
	v_add_u32_e32 v63, s3, v3
	s_movk_i32 s3, 0x80
	v_and_b32_e32 v3, 0x3fffffc0, v0
	v_lshlrev_b32_e32 v2, 2, v32
	v_cmp_gt_i32_e64 s[6:7], s3, v0
	v_lshlrev_b32_e32 v3, 2, v3
	v_lshl_or_b32 v66, s10, 7, v1
	s_mov_b32 s3, 0x9000
	v_ashrrev_i32_e32 v64, 6, v0
	v_add3_u32 v65, 0, v3, v2
	v_mad_u64_u32 v[2:3], s[10:11], v66, s3, 0
	v_and_b32_e32 v0, 15, v0
	v_lshl_or_b32 v2, v0, 4, v2
	v_lshl_add_u64 v[0:1], s[8:9], 0, v[2:3]
	s_mov_b64 s[8:9], 0x90000
	v_cmp_gt_u32_e64 s[4:5], 16, v32
	v_mov_b32_e32 v35, 0
	v_lshl_add_u64 v[36:37], v[0:1], 0, s[8:9]
	s_movk_i32 s33, 0x1000
	s_mov_b32 s40, 0xfff94000
	s_mov_b32 s41, 0xfffb8000
	s_mov_b32 s52, 0xfffdc000
	s_mov_b32 s53, 0x24000
	s_mov_b32 s54, 0x48000
	s_mov_b32 s55, 0x6c000
	s_mov_b64 s[48:49], 0x120000
	v_lshlrev_b32_e32 v38, 2, v32
	s_branch .LBB0_21

; #define LAS __attribute__((address_space(3)))
; __device__ __forceinline__ unsigned pk2(float lo, float hi) { return f2bf(lo) | (f2bf(hi) << 16); }
; #define ARG_IN(i) argp(i)
; template <bool MIX>
; __device__ __forceinline__ void norm_phase(const float* xin, int l, int sub, LAS unsigned char* lds, int vcu, int G, int tid, int wave, int lane) {
;     unsigned char* ws_ = ARG_WS; const float* gain = ARG_IN(4) + (size_t)(l * 3 + sub) * 1024; const float* MOD = (const float*)(ws_ + WS_MOD);
;     const float* shift = MOD + (size_t)(l * 2) * 9216 + (3 * sub) * 1024; const float* scale = shift + 1024;
;     bf16* XN = (bf16*)(ws_ + WS_XN);
;     LAS float* wfs = (LAS float*)lds; LAS float* lfs = (LAS float*)(lds + 32768);
;     if (MIX) { const float* WF = (const float*)(ws_ + WS_WF); for (int i = tid; i < 8192; i += 512) wfs[i] = WF[i]; __syncthreads(); }
;     for (int blk = vcu; blk < 256; blk += G) {
;         const int b = blk >> 7;
; #pragma unroll (MIX ? 2 : 4)
;         for (int i = 0; i < 8; ++i) { const int rl = wave * 8 + i, row = blk * 64 + rl;
;             const f32x4* xr = (const f32x4*)(xin + (size_t)row * 1024) + lane;
;             f32x4 v[4]; float ss = 0.f;
; #pragma unroll
;             for (int j = 0; j < 4; ++j) { v[j] = xr[64 * j]; ss += (v[j].x * v[j].x + v[j].y * v[j].y) + (v[j].z * v[j].z + v[j].w * v[j].w); }
;             const float rstd = 1.0f / sqrtf(wave_sum(ss) * (1.0f / 1024.0f) + 1e-6f);
;             unsigned long long* o8 = (unsigned long long*)(XN + (size_t)row * 1024) + lane;
; #pragma unroll
;             for (int j = 0; j < 4; ++j) { const f32x4 g = ((const f32x4*)gain)[64 * j + lane], sc = ((const f32x4*)(scale + b * 9216))[64 * j + lane], sh = ((const f32x4*)(shift + b * 9216))[64 * j + lane];
;                 v[j] = (v[j] * rstd * g) * (1.0f + sc) + sh;
;                 o8[64 * j] = (unsigned long long)pk2(v[j].x, v[j].y) | ((unsigned long long)pk2(v[j].z, v[j].w) << 32); }
.LBB0_80:
	s_or_b64 exec, exec, s[4:5]
	s_waitcnt lgkmcnt(0)
	s_barrier
	s_load_dwordx2 s[0:1], s[96:97], 0x98
	v_mov_b32_e32 v0, v219
	s_waitcnt lgkmcnt(0)
	s_mov_b32 s1, s71
	s_mov_b32 s3, s2
	s_load_dwordx2 s[8:9], s[96:97], 0
	s_load_dwordx2 s[4:5], s[96:97], 0x88
	s_load_dwordx2 s[6:7], s[96:97], 32
	s_waitcnt lgkmcnt(0)
	s_cmpk_gt_i32 s1, 0xff
	s_cbranch_scc1 .LBB0_85
	v_mbcnt_hi_u32_b32 v3, -1, v76
	v_and_b32_e32 v4, 64, v3
	v_add_u32_e32 v4, 64, v4
	v_xor_b32_e32 v5, 1, v3
	v_cmp_lt_i32_e32 vcc, v5, v4
	v_and_b32_e32 v2, 63, v0
	v_mov_b32_e32 v1, 0
	v_cndmask_b32_e32 v5, v3, v5, vcc
	v_lshlrev_b32_e32 v38, 2, v5
	v_xor_b32_e32 v5, 2, v3
	v_cmp_lt_i32_e32 vcc, v5, v4
	v_lshlrev_b32_e32 v0, 4, v2
	v_lshlrev_b32_e32 v2, 3, v2
	v_cndmask_b32_e32 v5, v3, v5, vcc
	v_lshlrev_b32_e32 v39, 2, v5
	v_xor_b32_e32 v5, 4, v3
	v_cmp_lt_i32_e32 vcc, v5, v4
	v_readlane_b32 s3, v255, 4
	v_lshl_add_u64 v[18:19], s[4:5], 0, v[0:1]
	v_cndmask_b32_e32 v5, v3, v5, vcc
	v_lshlrev_b32_e32 v40, 2, v5
	v_xor_b32_e32 v5, 8, v3
	v_cmp_lt_i32_e32 vcc, v5, v4
	s_lshl_b32 s3, s3, 3
	v_lshl_add_u64 v[12:13], s[8:9], 0, v[0:1]
	v_cndmask_b32_e32 v5, v3, v5, vcc
	v_lshlrev_b32_e32 v41, 2, v5
	v_xor_b32_e32 v5, 16, v3
	v_cmp_lt_i32_e32 vcc, v5, v4
	s_mov_b64 s[8:9], 0x3600000
	v_lshl_add_u64 v[16:17], s[6:7], 0, v[0:1]
	v_cndmask_b32_e32 v5, v3, v5, vcc
	v_lshlrev_b32_e32 v42, 2, v5
	v_xor_b32_e32 v5, 32, v3
	v_cmp_lt_i32_e32 vcc, v5, v4
	v_lshlrev_b32_e64 v0, 6, s0
	v_mov_b32_e32 v44, 0x358637bd
	v_cndmask_b32_e32 v3, v3, v5, vcc
	v_lshlrev_b32_e32 v43, 2, v3
	v_mov_b32_e32 v3, v1
	v_lshl_add_u64 v[2:3], s[4:5], 0, v[2:3]
	s_mov_b64 s[4:5], 0x1000
	v_lshl_add_u64 v[20:21], v[18:19], 0, s[4:5]
	s_lshl_b32 s4, s1, 6
	v_lshl_add_u64 v[14:15], v[2:3], 0, s[8:9]
	s_add_i32 s3, s4, s3
	v_readfirstlane_b32 s16, v0
	s_mov_b32 s17, 0xf800000
	v_mov_b32_e32 v45, 0x260
	s_movk_i32 s18, 0x7fff
	s_mov_b32 s19, 0xffff0000

; #define LAS __attribute__((address_space(3)))
; __device__ __forceinline__ float silu_f(float x) { return x / (1.0f + __expf(-x)); }
; #define ARG_IN(i) argp(i)
; __device__ __forceinline__ void mod_phase(int j0, int j1, LAS unsigned char* lds, int vcu, int G, int tid, int wave, int lane) {
;     unsigned char* ws_ = ARG_WS; float* MOD = (float*)(ws_ + WS_MOD); const float* c = ARG_IN(1); const float* w_ada = ARG_IN(2); const float* b_ada = ARG_IN(3);
;     LAS float* part = (LAS float*)lds;
;     for (int job = j0 + vcu; job < j1; job += G) {
;         const int lm = job / 144, colbase = (job % 144) * 64, kk = lane >> 4, c4 = lane & 15;
;         f32x4 acc0 = {0.f, 0.f, 0.f, 0.f}, acc1 = {0.f, 0.f, 0.f, 0.f};
;         const float* wp = w_ada + ((size_t)lm * 1024 + wave * 128 + kk) * 9216 + colbase + 4 * c4;
; #pragma unroll 8
;         for (int i = 0; i < 32; ++i) { const int k = wave * 128 + 4 * i + kk; const f32x4 wv = *(const f32x4*)(wp + (size_t)i * 4 * 9216); const float a0 = silu_f(c[k]), a1 = silu_f(c[1024 + k]); acc0 += a0 * wv; acc1 += a1 * wv; }
.LBB0_85:
	s_load_dwordx2 s[0:1], s[96:97], 0x98
	s_waitcnt lgkmcnt(0)
	s_mov_b32 s1, s71
	s_mov_b32 s3, s2
	v_mov_b32_e32 v0, v219
	s_load_dwordx2 s[42:43], s[96:97], 0x88
	s_load_dwordx2 s[44:45], s[96:97], 8
	s_load_dwordx2 s[8:9], s[96:97], 16
	s_load_dwordx2 s[46:47], s[96:97], 24
	s_waitcnt lgkmcnt(0)
	s_cmpk_gt_i32 s1, 0xff
	s_cbranch_scc1 .LBB0_94
	v_mbcnt_hi_u32_b32 v3, -1, v76
	v_and_b32_e32 v5, 64, v3
	v_xor_b32_e32 v4, 16, v3
	v_add_u32_e32 v5, 64, v5
	v_cmp_lt_i32_e32 vcc, v4, v5
	v_readlane_b32 s10, v255, 4
	s_lshl_b32 s3, s10, 9
	v_cndmask_b32_e32 v4, v3, v4, vcc
	v_lshlrev_b32_e32 v33, 2, v4
	v_xor_b32_e32 v4, 32, v3
	v_cmp_lt_i32_e32 vcc, v4, v5
	s_add_i32 s3, s3, 0
	v_and_b32_e32 v32, 63, v0
	v_cndmask_b32_e32 v3, v3, v4, vcc
	v_lshlrev_b32_e32 v62, 2, v3
	v_lshlrev_b32_e32 v3, 4, v0
	v_and_b32_e32 v3, 0xf0, v3
	v_bfe_u32 v1, v0, 4, 2
	v_add_u32_e32 v63, s3, v3
	s_movk_i32 s3, 0x80
	v_and_b32_e32 v3, 0x3fffffc0, v0
	v_lshlrev_b32_e32 v2, 2, v32
	v_cmp_gt_i32_e64 s[6:7], s3, v0
	v_lshlrev_b32_e32 v3, 2, v3
	v_lshl_or_b32 v66, s10, 7, v1
	s_mov_b32 s3, 0x9000
	v_ashrrev_i32_e32 v64, 6, v0
	v_add3_u32 v65, 0, v3, v2
	v_mad_u64_u32 v[2:3], s[10:11], v66, s3, 0
	v_and_b32_e32 v0, 15, v0
	v_lshl_or_b32 v2, v0, 4, v2
	v_lshl_add_u64 v[0:1], s[8:9], 0, v[2:3]
	s_mov_b64 s[8:9], 0x90000
	s_add_i32 s1, s1, 32
	v_cmp_gt_u32_e64 s[4:5], 16, v32
	v_mov_b32_e32 v35, 0
	v_lshl_add_u64 v[36:37], v[0:1], 0, s[8:9]
	s_movk_i32 s33, 0x1000
	s_mov_b32 s40, 0xfff94000
	s_mov_b32 s41, 0xfffb8000
	s_mov_b32 s52, 0xfffdc000
	s_mov_b32 s53, 0x24000
	s_mov_b32 s54, 0x48000
	s_mov_b32 s55, 0x6c000
	s_mov_b64 s[48:49], 0x120000
	v_lshlrev_b32_e32 v38, 2, v32
	s_branch .LBB0_88

;     __device__ __forceinline__ bool next(int i, Unit& u) const { Unit t; if (!S0.next(i / 3, t)) return false; u.pm = t.pm; u.pn = 4 * (i % 3) + t.pn; u.roff = 0; u.nai = 2; return true; }
; #define ARG_IN(i) argp(i)
; #define FRESH() int G_ = G, bx_ = bx, vcu_ = vcu, tid_ = tid; asm volatile("" : "+s"(G_), "+s"(bx_), "+s"(vcu_), "+v"(tid_)); const int lane_ = tid_ & 63; (void)lane_; (void)bx_
;     __host__ __device__ bool next(int i, Unit& u) const {
;         long L = (long)i * G + c; u.roff = 0; u.nai = 2;
;         const int full = nwg / G;
;         if (tail && (nwg - full * G) * 2 == G && i >= full) { if (i > full) return false; L = (long)full * G + (c >> 1); u.roff = 128 * (c & 1); u.nai = 1; }
;         if (L >= nwg) return false;
;         int wgid = (int)L; { const int q = nwg / NXCD, r = nwg % NXCD, xcd = wgid % NXCD, off = wgid / NXCD; wgid = (xcd < r ? xcd * (q + 1) : r * (q + 1) + (xcd - r) * q) + off; }
;         const int nig = WGM * nN, gid = wgid / nig, fm = gid * WGM, gsz = (nM - fm) < WGM ? (nM - fm) : WGM;
;         u.pm = fm + ((wgid % nig) % gsz); u.pn = (wgid % nig) / gsz; return true;
; __global__ void __launch_bounds__(NWAVES * 64, 2) mk_fwd(Args) {
;     ...
;                 FRESH(); unsigned char* ws = ARG_WS; float* outp = ARG_OUT;
;                 pg8::Gemm g{(const pbf*)(ws + WS_BIG), (const pbf*)(ws + WS_WD) + (size_t)f * 1024 * FF, M, D, FF, NOSPLIT, 0}; pg8::StaticOrder S; S.init(M, D, G_, bx_);
;                 const int nl = (f == 0) ? l : 1, nsub = (f == 0) ? 1 : 0, bank = (f == 0) ? 3 + l : 2, donorm = (f == 0 || l == 0) ? 1 : 0;
;                 const float* ng_ = ARG_IN(4) + (size_t)(nl * 3 + nsub) * 1024; const float* xin_ = ARG_IN(0);
;                 const float* nm_ = (const float*)(ws + WS_MOD) + (size_t)(nl * 2) * 9216 + (size_t)(3 * nsub) * 1024;
;                 pg8::EpiResid E{(f == 0 && l == 0) ? xin_ : (const float*)outp, outp, (const float*)(ws + WS_MOD) + (size_t)(l * 2) * 9216 + (f == 0 ? 2 : 8) * 1024,
;                                 (pbf*)(ws + WS_XN), ng_, nm_, nm_ + 1024, (float*)(ws + WS_XBUF), (unsigned*)(ws + WS_CTL) + 4096 + bank * 4096, 0.5f, donorm};
.LBB0_361:
	s_or_b64 exec, exec, s[4:5]
	s_xor_b64 s[0:1], s[6:7], -1
	v_writelane_b32 v255, s0, 32
	v_mov_b32_e32 v0, v219
	s_waitcnt lgkmcnt(0)
	v_writelane_b32 v255, s1, 33
	s_barrier
	v_readlane_b32 s0, v255, 0
	v_readlane_b32 s1, v255, 1
	s_mov_b32 s6, s0
	s_mov_b32 s1, s71
	s_mov_b32 s0, s2
	s_load_dwordx2 s[14:15], s[96:97], 0x88
	s_load_dwordx2 s[20:21], s[96:97], 0x80
	s_load_dwordx2 s[16:17], s[96:97], 32
	s_load_dwordx2 s[22:23], s[96:97], 0
	s_waitcnt lgkmcnt(0)
	s_xor_b64 s[10:11], s[12:13], -1
	v_mov_b32_e32 v153, v219
	s_cmpk_gt_i32 s0, 0xff
	v_readfirstlane_b32 s36, v153
	s_cbranch_scc1 .LBB0_425
	s_ashr_i32 s1, s0, 31
	s_lshr_b32 s4, s1, 29
	s_add_i32 s9, s0, s4
	s_and_b32 s4, s9, -8
	s_sub_i32 s8, s0, s4
	s_cmp_gt_i32 s8, -1
	s_mov_b64 s[4:5], -1
	s_cbranch_scc0 .LBB0_364
	s_lshl_b32 s7, s8, 5
	s_mov_b64 s[4:5], 0

; #define LAS __attribute__((address_space(3)))
; #define ARG_IN(i) argp(i)
; __device__ __forceinline__ void f_phase(int l, LAS unsigned char* lds, int vcu, int G, int tid, int wave, int lane) {
;     unsigned char* ws_ = ARG_WS; const bf16* XN = (const bf16*)(ws_ + WS_XN); const float* fb = ARG_IN(11) + l * 8;
;     LAS float* wfs = (LAS float*)lds; LAS float* lfs = (LAS float*)(lds + 32768);
;     { const float* WF = (const float*)(ws_ + WS_WF); for (int i = tid; i < 8192; i += 512) wfs[i] = WF[i]; __syncthreads(); }
.LBB0_478:
	s_or_b64 exec, exec, s[4:5]
	s_andn2_b64 vcc, exec, s[10:11]
	s_waitcnt lgkmcnt(0)
	s_barrier
	s_cbranch_vccnz .LBB0_272
	v_readlane_b32 s0, v255, 0
	s_mov_b32 s3, s2
	v_mov_b32_e32 v10, v219
	s_mov_b32 s41, s0
	s_mov_b32 s30, s71
	s_load_dwordx2 s[10:11], s[96:97], 0x88
	s_load_dwordx2 s[4:5], s[96:97], 0x58
	s_waitcnt lgkmcnt(0)
	s_movk_i32 s0, 0x2000
	v_cmp_gt_i32_e32 vcc, s0, v10
	v_readlane_b32 s1, v255, 1
	s_and_saveexec_b64 s[6:7], vcc
	s_cbranch_execz .LBB0_487
	v_max_i32_e32 v0, 0x1e00, v10
	v_sub_u32_e32 v0, v0, v10
	s_add_u32 s8, s10, 0x40000
	v_add_u32_e32 v0, 0x1ff, v0
	s_movk_i32 s0, 0x1ff
	s_addc_u32 s9, s11, 0
	v_cmp_lt_u32_e32 vcc, s0, v0
	s_mov_b64 s[14:15], -1
	v_mov_b32_e32 v2, v10
	s_and_saveexec_b64 s[12:13], vcc
	s_cbranch_execz .LBB0_484
	v_lshrrev_b32_e32 v0, 9, v0
	v_add_u32_e32 v0, 1, v0
	v_and_b32_e32 v4, 0xfffffe, v0
	v_add_u32_e32 v11, 0x200, v10
	v_lshl_add_u32 v5, v10, 2, 0
	s_mov_b64 s[14:15], 0
	v_mov_b32_e32 v6, v4
	v_mov_b64_e32 v[2:3], v[10:11]

;     __device__ __forceinline__ bool next(int i, Unit& u) const { Unit t; if (!S0.next(i / 3, t)) return false; u.pm = t.pm; u.pn = 4 * (i % 3) + t.pn; u.roff = 0; u.nai = 2; return true; }
; #define ARG_IN(i) argp(i)
; #define FRESH() int G_ = G, bx_ = bx, vcu_ = vcu, tid_ = tid; asm volatile("" : "+s"(G_), "+s"(bx_), "+s"(vcu_), "+v"(tid_)); const int lane_ = tid_ & 63; (void)lane_; (void)bx_
;     __host__ __device__ bool next(int i, Unit& u) const {
;         long L = (long)i * G + c; u.roff = 0; u.nai = 2;
;         const int full = nwg / G;
;         if (tail && (nwg - full * G) * 2 == G && i >= full) { if (i > full) return false; L = (long)full * G + (c >> 1); u.roff = 128 * (c & 1); u.nai = 1; }
;         if (L >= nwg) return false;
;         int wgid = (int)L; { const int q = nwg / NXCD, r = nwg % NXCD, xcd = wgid % NXCD, off = wgid / NXCD; wgid = (xcd < r ? xcd * (q + 1) : r * (q + 1) + (xcd - r) * q) + off; }
;         const int nig = WGM * nN, gid = wgid / nig, fm = gid * WGM, gsz = (nM - fm) < WGM ? (nM - fm) : WGM;
;         u.pm = fm + ((wgid % nig) % gsz); u.pn = (wgid % nig) / gsz; return true;
; __global__ void __launch_bounds__(NWAVES * 64, 2) mk_fwd(Args) {
;     ...
;                     FRESH(); unsigned char* ws = ARG_WS; float* outp = ARG_OUT;
;                     pg8::Gemm g{(const pbf*)(ws + WS_MG), (const pbf*)(ws + WS_WO), M, D, D, NOSPLIT, 0}; pg8::StaticOrder S; S.init(M, D, G_, bx_);
;                     const float* ng_ = ARG_IN(4) + (size_t)(l * 3 + 2) * 1024;
;                     pg8::EpiResid E{outp, outp, (const float*)(ws + WS_MOD) + (size_t)(l * 2) * 9216 + 5 * 1024,
;                                     (pbf*)(ws + WS_XN), ng_, (const float*)(ws + WS_MOD) + (size_t)(l * 2) * 9216 + 6 * 1024, (const float*)(ws + WS_MOD) + (size_t)(l * 2) * 9216 + 7 * 1024, (float*)(ws + WS_XBUF), (unsigned*)(ws + WS_CTL) + 4096 + l * 4096, 1.0f, 1};
;     ...
;                     pg8::gemm_phase<pg8::EpiResid, pg8::StaticOrder, false, true>(lds, g, S, E);
.LBB0_1134:
	s_or_b64 exec, exec, s[4:5]
	v_readlane_b32 s0, v255, 0
	v_readlane_b32 s1, v255, 1
	s_mov_b32 s6, s0
	s_mov_b32 s1, s71
	s_mov_b32 s0, s2
	v_mov_b32_e32 v0, v219
	s_waitcnt lgkmcnt(0)
	s_barrier
	s_load_dwordx2 s[8:9], s[96:97], 0x88
	s_load_dwordx2 s[16:17], s[96:97], 0x80
	s_load_dwordx2 s[10:11], s[96:97], 32
	s_waitcnt lgkmcnt(0)
	v_mov_b32_e32 v173, v219
	s_cmpk_gt_i32 s0, 0xff
	v_readfirstlane_b32 s3, v173
	s_cbranch_scc1 .LBB0_1194
	s_ashr_i32 s1, s0, 31
	s_lshr_b32 s4, s1, 29
	s_add_i32 s13, s0, s4
	s_and_b32 s4, s13, -8
	s_sub_i32 s12, s0, s4
	s_cmp_gt_i32 s12, -1
	s_mov_b64 s[4:5], -1
	s_cbranch_scc0 .LBB0_1137
	s_lshl_b32 s7, s12, 5
	s_mov_b64 s[4:5], 0
